# u_hy tiles of the input projection: LDS-transposed epilogue (ds_read_b64_tr_b16) with 16-byte stores instead of 2-byte stores; +28 KiB static LDS
# speedup vs baseline: 1.0079x; 1.0079x over previous
.LBB0_247:
	s_sub_u32 s98, s8, 0x200
	s_cmp_lt_u32 s98, 0x600
	s_cbranch_scc1 .Luhy_epi
	v_add_u32_e32 v150, s4, v158
	v_ashrrev_i32_e32 v154, 11, v150
	v_add_u32_e32 v146, s8, v160
	v_ashrrev_i32_e32 v151, 31, v150
	v_ashrrev_i32_e32 v155, 31, v154
	v_and_b32_e32 v164, 0x7ff, v150
	v_lshlrev_b64 v[152:153], 12, v[150:151]
	v_lshlrev_b64 v[156:157], 12, v[154:155]
	v_cmp_lt_i32_e64 s[4:5], s71, v146
	s_and_saveexec_b64 s[2:3], s[4:5]
	s_xor_b64 s[8:9], exec, s[2:3]
	s_cbranch_execz .LBB0_253
	v_cmp_lt_u32_e32 vcc, s70, v146
	s_and_saveexec_b64 s[2:3], vcc
	s_xor_b64 s[40:41], exec, s[2:3]
	s_cbranch_execz .LBB0_250
	v_mul_f32_e32 v136, 0xbfb8aa3b, v124
	v_mul_f32_e32 v147, 0xbfb8aa3b, v120
	v_mul_f32_e32 v148, 0xbfb8aa3b, v125
	v_mul_f32_e32 v149, 0xbfb8aa3b, v121
	v_exp_f32_e32 v136, v136
	v_exp_f32_e32 v147, v147
	v_exp_f32_e32 v148, v148
	v_exp_f32_e32 v149, v149
	v_mul_f32_e32 v151, 0xbfb8aa3b, v126
	v_mul_f32_e32 v155, 0xbfb8aa3b, v122
	v_mul_f32_e32 v165, 0xbfb8aa3b, v127
	v_mul_f32_e32 v166, 0xbfb8aa3b, v123
	v_exp_f32_e32 v151, v151
	v_exp_f32_e32 v155, v155
	v_exp_f32_e32 v165, v165
	v_exp_f32_e32 v166, v166
	v_add_f32_e32 v136, 1.0, v136
	v_add_f32_e32 v147, 1.0, v147
	v_add_f32_e32 v148, 1.0, v148
	v_add_f32_e32 v149, 1.0, v149
	v_rcp_f32_e32 v136, v136
	v_rcp_f32_e32 v147, v147
	v_rcp_f32_e32 v148, v148
	v_rcp_f32_e32 v149, v149
	v_add_f32_e32 v151, 1.0, v151
	v_add_f32_e32 v155, 1.0, v155
	v_add_f32_e32 v165, 1.0, v165
	v_add_f32_e32 v166, 1.0, v166
	v_rcp_f32_e32 v151, v151
	v_rcp_f32_e32 v155, v155
	v_rcp_f32_e32 v165, v165
	v_rcp_f32_e32 v169, v166
	v_cvt_pk_bf16_f32 v166, v136, v148
	v_cvt_pk_bf16_f32 v168, v147, v149
	v_lshl_add_u64 v[148:149], s[24:25], 0, v[152:153]
	v_mov_b32_e32 v147, v137
	v_cvt_pk_bf16_f32 v167, v151, v165
	v_cvt_pk_bf16_f32 v169, v155, v169
	v_lshl_add_u64 v[148:149], v[146:147], 1, v[148:149]
	global_store_dwordx4 v[148:149], v[166:169], off offset:-4096 nt

.Luhy_join:
	s_mov_b64 s[4:5], -1
	s_and_b64 vcc, exec, s[0:1]
	s_cbranch_vccz .LBB0_236

.Luhy_epi:
	v_and_b32_e32 v136, 63, v193
	v_lshrrev_b32_e32 v156, 6, v193
	v_mul_u32_u24_e32 v157, 0xe00, v156
	v_add_u32_e32 v157, 0x21000, v157
	v_and_b32_e32 v146, 15, v136
	v_mul_u32_u24_e32 v146, 0x50, v146
	v_lshrrev_b32_e32 v147, 4, v136
	v_lshl_add_u32 v146, v147, 4, v146
	v_add_u32_e32 v146, v146, v157
	v_lshrrev_b32_e32 v168, 5, v136
	v_bfe_u32 v169, v136, 2, 2
	v_lshl_add_u32 v168, v168, 3, v169
	v_mul_u32_u24_e32 v168, 0x50, v168
	v_and_b32_e32 v169, 1, v147
	v_lshl_add_u32 v168, v169, 5, v168
	v_and_b32_e32 v147, 3, v136
	v_lshl_add_u32 v147, v147, 3, v168
	v_add_u32_e32 v147, v147, v157
	v_and_b32_e32 v168, 15, v136
	v_lshl_add_u32 v168, v169, 4, v168
	v_lshlrev_b32_e32 v168, 16, v168
	v_lshrrev_b32_e32 v169, 5, v136
	v_lshl_add_u32 v168, v169, 4, v168
	v_readfirstlane_b32 s98, v156
	s_nop 3
	s_and_b32 s99, s98, 3
	s_lshr_b32 s98, s98, 2
	s_lshl_b32 s99, s99, 5
	s_add_i32 s99, s99, s8
	s_sub_i32 s99, s99, 0x200
	s_lshl_b32 s99, s99, 16
	s_lshl_b32 s98, s98, 6
	s_add_i32 s98, s98, s4
	s_lshl_b32 s98, s98, 1
	s_add_i32 s98, s98, s99
	v_add_u32_e32 v148, s98, v168
	v_mov_b32_e32 v149, 0
	v_lshl_add_u64 v[148:149], s[20:21], 0, v[148:149]
	s_mov_b32 s100, 0x800000
	s_mov_b32 s101, 0
	v_lshl_add_u64 v[150:151], v[148:149], 0, s[100:101]
	v_cvt_pk_bf16_f32 v152, v124, v125
	v_cvt_pk_bf16_f32 v153, v126, v127
	v_cvt_pk_bf16_f32 v154, v120, v121
	v_cvt_pk_bf16_f32 v155, v122, v123
	ds_write_b128 v146, v[152:155]
	v_cvt_pk_bf16_f32 v164, v108, v109
	v_cvt_pk_bf16_f32 v165, v110, v111
	v_cvt_pk_bf16_f32 v166, v104, v105
	v_cvt_pk_bf16_f32 v167, v106, v107
	ds_write_b128 v146, v[164:167] offset:1280
	ds_read_b64_tr_b16 v[164:165], v147
	ds_read_b64_tr_b16 v[166:167], v147 offset:320
	ds_read_b64_tr_b16 v[152:153], v147 offset:1280
	ds_read_b64_tr_b16 v[154:155], v147 offset:1600
	s_waitcnt lgkmcnt(0)
	global_store_dwordx4 v[148:149], v[164:167], off
	global_store_dwordx4 v[148:149], v[152:155], off offset:32
	s_nop 1
	v_cvt_pk_bf16_f32 v152, v92, v93
	v_cvt_pk_bf16_f32 v153, v94, v95
	v_cvt_pk_bf16_f32 v154, v88, v89
	v_cvt_pk_bf16_f32 v155, v90, v91
	ds_write_b128 v146, v[152:155]
	v_cvt_pk_bf16_f32 v164, v76, v77
	v_cvt_pk_bf16_f32 v165, v78, v79
	v_cvt_pk_bf16_f32 v166, v72, v73
	v_cvt_pk_bf16_f32 v167, v74, v75
	ds_write_b128 v146, v[164:167] offset:1280
	ds_read_b64_tr_b16 v[164:165], v147
	ds_read_b64_tr_b16 v[166:167], v147 offset:320
	ds_read_b64_tr_b16 v[152:153], v147 offset:1280
	ds_read_b64_tr_b16 v[154:155], v147 offset:1600
	s_waitcnt lgkmcnt(0)
	global_store_dwordx4 v[148:149], v[164:167], off offset:64
	global_store_dwordx4 v[148:149], v[152:155], off offset:96
	s_nop 1
	v_cvt_pk_bf16_f32 v152, v116, v117
	v_cvt_pk_bf16_f32 v153, v118, v119
	v_cvt_pk_bf16_f32 v154, v112, v113
	v_cvt_pk_bf16_f32 v155, v114, v115
	ds_write_b128 v146, v[152:155]
	v_cvt_pk_bf16_f32 v164, v100, v101
	v_cvt_pk_bf16_f32 v165, v102, v103
	v_cvt_pk_bf16_f32 v166, v96, v97
	v_cvt_pk_bf16_f32 v167, v98, v99
	ds_write_b128 v146, v[164:167] offset:1280
	ds_read_b64_tr_b16 v[164:165], v147
	ds_read_b64_tr_b16 v[166:167], v147 offset:320
	ds_read_b64_tr_b16 v[152:153], v147 offset:1280
	ds_read_b64_tr_b16 v[154:155], v147 offset:1600
	s_waitcnt lgkmcnt(0)
	global_store_dwordx4 v[150:151], v[164:167], off
	global_store_dwordx4 v[150:151], v[152:155], off offset:32
	s_nop 1
	v_cvt_pk_bf16_f32 v152, v84, v85
	v_cvt_pk_bf16_f32 v153, v86, v87
	v_cvt_pk_bf16_f32 v154, v80, v81
	v_cvt_pk_bf16_f32 v155, v82, v83
	ds_write_b128 v146, v[152:155]
	v_cvt_pk_bf16_f32 v164, v68, v69
	v_cvt_pk_bf16_f32 v165, v70, v71
	v_cvt_pk_bf16_f32 v166, v64, v65
	v_cvt_pk_bf16_f32 v167, v66, v67
	ds_write_b128 v146, v[164:167] offset:1280
	ds_read_b64_tr_b16 v[164:165], v147
	ds_read_b64_tr_b16 v[166:167], v147 offset:320
	ds_read_b64_tr_b16 v[152:153], v147 offset:1280
	ds_read_b64_tr_b16 v[154:155], v147 offset:1600
	s_waitcnt lgkmcnt(0)
	global_store_dwordx4 v[150:151], v[164:167], off offset:64
	global_store_dwordx4 v[150:151], v[152:155], off offset:96
	s_nop 1
	v_cvt_pk_bf16_f32 v152, v60, v61
	v_cvt_pk_bf16_f32 v153, v62, v63
	v_cvt_pk_bf16_f32 v154, v56, v57
	v_cvt_pk_bf16_f32 v155, v58, v59
	ds_write_b128 v146, v[152:155]
	v_cvt_pk_bf16_f32 v164, v44, v45
	v_cvt_pk_bf16_f32 v165, v46, v47
	v_cvt_pk_bf16_f32 v166, v40, v41
	v_cvt_pk_bf16_f32 v167, v42, v43
	ds_write_b128 v146, v[164:167] offset:1280
	ds_read_b64_tr_b16 v[164:165], v147
	ds_read_b64_tr_b16 v[166:167], v147 offset:320
	ds_read_b64_tr_b16 v[152:153], v147 offset:1280
	ds_read_b64_tr_b16 v[154:155], v147 offset:1600
	s_waitcnt lgkmcnt(0)
	global_store_dwordx4 v[148:149], v[164:167], off offset:256
	global_store_dwordx4 v[148:149], v[152:155], off offset:288
	s_nop 1
	v_cvt_pk_bf16_f32 v152, v28, v29
	v_cvt_pk_bf16_f32 v153, v30, v31
	v_cvt_pk_bf16_f32 v154, v24, v25
	v_cvt_pk_bf16_f32 v155, v26, v27
	ds_write_b128 v146, v[152:155]
	v_cvt_pk_bf16_f32 v164, v12, v13
	v_cvt_pk_bf16_f32 v165, v14, v15
	v_cvt_pk_bf16_f32 v166, v8, v9
	v_cvt_pk_bf16_f32 v167, v10, v11
	ds_write_b128 v146, v[164:167] offset:1280
	ds_read_b64_tr_b16 v[164:165], v147
	ds_read_b64_tr_b16 v[166:167], v147 offset:320
	ds_read_b64_tr_b16 v[152:153], v147 offset:1280
	ds_read_b64_tr_b16 v[154:155], v147 offset:1600
	s_waitcnt lgkmcnt(0)
	global_store_dwordx4 v[148:149], v[164:167], off offset:320
	global_store_dwordx4 v[148:149], v[152:155], off offset:352
	s_nop 1
	v_cvt_pk_bf16_f32 v152, v52, v53
	v_cvt_pk_bf16_f32 v153, v54, v55
	v_cvt_pk_bf16_f32 v154, v48, v49
	v_cvt_pk_bf16_f32 v155, v50, v51
	ds_write_b128 v146, v[152:155]
	v_cvt_pk_bf16_f32 v164, v36, v37
	v_cvt_pk_bf16_f32 v165, v38, v39
	v_cvt_pk_bf16_f32 v166, v32, v33
	v_cvt_pk_bf16_f32 v167, v34, v35
	ds_write_b128 v146, v[164:167] offset:1280
	ds_read_b64_tr_b16 v[164:165], v147
	ds_read_b64_tr_b16 v[166:167], v147 offset:320
	ds_read_b64_tr_b16 v[152:153], v147 offset:1280
	ds_read_b64_tr_b16 v[154:155], v147 offset:1600
	s_waitcnt lgkmcnt(0)
	global_store_dwordx4 v[150:151], v[164:167], off offset:256
	global_store_dwordx4 v[150:151], v[152:155], off offset:288
	s_nop 1
	v_cvt_pk_bf16_f32 v152, v20, v21
	v_cvt_pk_bf16_f32 v153, v22, v23
	v_cvt_pk_bf16_f32 v154, v16, v17
	v_cvt_pk_bf16_f32 v155, v18, v19
	ds_write_b128 v146, v[152:155]
	v_cvt_pk_bf16_f32 v164, v4, v5
	v_cvt_pk_bf16_f32 v165, v6, v7
	v_cvt_pk_bf16_f32 v166, v0, v1
	v_cvt_pk_bf16_f32 v167, v2, v3
	ds_write_b128 v146, v[164:167] offset:1280
	ds_read_b64_tr_b16 v[164:165], v147
	ds_read_b64_tr_b16 v[166:167], v147 offset:320
	ds_read_b64_tr_b16 v[152:153], v147 offset:1280
	ds_read_b64_tr_b16 v[154:155], v147 offset:1600
	s_waitcnt lgkmcnt(0)
	global_store_dwordx4 v[150:151], v[164:167], off offset:320
	global_store_dwordx4 v[150:151], v[152:155], off offset:352
	s_nop 1
	s_branch .Luhy_join

	.amdhsa_kernel _Z4mega6Params
		.amdhsa_group_segment_fixed_size 28672
		.amdhsa_private_segment_fixed_size 0
		.amdhsa_kernarg_size 544
		.amdhsa_user_sgpr_count 2
		.amdhsa_user_sgpr_dispatch_ptr 0
		.amdhsa_user_sgpr_queue_ptr 0
		.amdhsa_user_sgpr_kernarg_segment_ptr 1
		.amdhsa_user_sgpr_dispatch_id 0
		.amdhsa_user_sgpr_kernarg_preload_length 0
		.amdhsa_user_sgpr_kernarg_preload_offset 0
		.amdhsa_user_sgpr_private_segment_size 0
		.amdhsa_uses_dynamic_stack 0
		.amdhsa_enable_private_segment 0
		.amdhsa_system_sgpr_workgroup_id_x 1
		.amdhsa_system_sgpr_workgroup_id_y 0
		.amdhsa_system_sgpr_workgroup_id_z 0
		.amdhsa_system_sgpr_workgroup_info 0
		.amdhsa_system_vgpr_workitem_id 2
		.amdhsa_next_free_vgpr 249
		.amdhsa_next_free_sgpr 102
		.amdhsa_accum_offset 252
		.amdhsa_reserve_vcc 1
		.amdhsa_float_round_mode_32 0
		.amdhsa_float_round_mode_16_64 0
		.amdhsa_float_denorm_mode_32 3
		.amdhsa_float_denorm_mode_16_64 3
		.amdhsa_dx10_clamp 1
		.amdhsa_ieee_mode 1
		.amdhsa_fp16_overflow 0
		.amdhsa_tg_split 0
		.amdhsa_exception_fp_ieee_invalid_op 0
		.amdhsa_exception_fp_denorm_src 0
		.amdhsa_exception_fp_ieee_div_zero 0
		.amdhsa_exception_fp_ieee_overflow 0
		.amdhsa_exception_fp_ieee_underflow 0
		.amdhsa_exception_fp_ieee_inexact 0
		.amdhsa_exception_int_div_zero 0
	.end_amdhsa_kernel

amdhsa.kernels:
  - .agpr_count:     0
    .args:
      - .offset:         0
        .size:           288
        .value_kind:     by_value
      - .offset:         288
        .size:           4
        .value_kind:     hidden_block_count_x
      - .offset:         292
        .size:           4
        .value_kind:     hidden_block_count_y
      - .offset:         296
        .size:           4
        .value_kind:     hidden_block_count_z
      - .offset:         300
        .size:           2
        .value_kind:     hidden_group_size_x
      - .offset:         302
        .size:           2
        .value_kind:     hidden_group_size_y
      - .offset:         304
        .size:           2
        .value_kind:     hidden_group_size_z
      - .offset:         306
        .size:           2
        .value_kind:     hidden_remainder_x
      - .offset:         308
        .size:           2
        .value_kind:     hidden_remainder_y
      - .offset:         310
        .size:           2
        .value_kind:     hidden_remainder_z
      - .offset:         328
        .size:           8
        .value_kind:     hidden_global_offset_x
      - .offset:         336
        .size:           8
        .value_kind:     hidden_global_offset_y
      - .offset:         344
        .size:           8
        .value_kind:     hidden_global_offset_z
      - .offset:         352
        .size:           2
        .value_kind:     hidden_grid_dims
      - .offset:         376
        .size:           8
        .value_kind:     hidden_multigrid_sync_arg
      - .offset:         408
        .size:           4
        .value_kind:     hidden_dynamic_lds_size
    .group_segment_fixed_size: 28672
    .kernarg_segment_align: 8
    .kernarg_segment_size: 544
    .language:       OpenCL C
    .language_version:
      - 2
      - 0
    .max_flat_workgroup_size: 512
    .name:           _Z4mega6Params
    .private_segment_fixed_size: 0
    .sgpr_count:     108
    .sgpr_spill_count: 24
    .symbol:         _Z4mega6Params.kd
    .uniform_work_group_size: 1
    .uses_dynamic_stack: false
    .vgpr_count:     249
    .vgpr_spill_count: 0
    .wavefront_size: 64
